# K-loop heads placed on 256-byte boundaries (branch over the padding)
# speedup vs baseline: 1.0017x; 1.0017x over previous
; template <class Epi, class Sched, bool ALIGN_EPI = false, bool SP2 = false>
; __device__ __forceinline__ void gemm_phase(PG8_LAS unsigned char* lds, const Gemm g, const Sched& S, const Epi& E) {
;     ...
;         asm volatile(".p2align 8");
;         for (int t = 0; t < nt; t += 2) {
;             const bool last = (t == nt - 2);
;             const char* a1 = cA + (size_t)(t + 1) * kstep;
;             const char* a2 = last ? nA : cA + (size_t)(t + 2) * kstep; const char* b2 = last ? nB : cB + (size_t)(t + 2) * kstep;
;             const char* a3 = a2 + kstep; const char* b3 = b2 + kstep;
;     ...
; #pragma unroll
;         for (int a = 0; a < 2; ++a)
; #pragma unroll
;             for (int b = 0; b < 2; ++b)
; #pragma unroll
;                 for (int m = 0; m < 4; ++m)
; #pragma unroll
;                     for (int n = 0; n < 2; ++n) acc[a][b][m][n] = (f32x4){0.f, 0.f, 0.f, 0.f};
;         cur = nxt; cA = nA; cB = nB; ++ui;
.LBB0_262:
	v_mov_b64_e32 v[0:1], 0
	v_mov_b64_e32 v[2:3], 0
	v_mov_b64_e32 v[4:5], 0
	v_mov_b64_e32 v[6:7], 0
	v_mov_b64_e32 v[8:9], 0
	v_mov_b64_e32 v[10:11], 0
	v_mov_b64_e32 v[12:13], 0
	v_mov_b64_e32 v[14:15], 0
	v_mov_b64_e32 v[16:17], 0
	v_mov_b64_e32 v[18:19], 0
	v_mov_b64_e32 v[20:21], 0
	v_mov_b64_e32 v[22:23], 0
	v_mov_b64_e32 v[24:25], 0
	v_mov_b64_e32 v[26:27], 0
	v_mov_b64_e32 v[28:29], 0
	v_mov_b64_e32 v[30:31], 0
	v_mov_b64_e32 v[32:33], 0
	v_mov_b64_e32 v[34:35], 0
	v_mov_b64_e32 v[36:37], 0
	v_mov_b64_e32 v[38:39], 0
	v_mov_b64_e32 v[40:41], 0
	v_mov_b64_e32 v[42:43], 0
	v_mov_b64_e32 v[44:45], 0
	v_mov_b64_e32 v[46:47], 0
	v_mov_b64_e32 v[48:49], 0
	v_mov_b64_e32 v[50:51], 0
	v_mov_b64_e32 v[52:53], 0
	v_mov_b64_e32 v[54:55], 0
	v_mov_b64_e32 v[56:57], 0
	v_mov_b64_e32 v[58:59], 0
	v_mov_b64_e32 v[60:61], 0
	v_mov_b64_e32 v[62:63], 0
	v_mov_b64_e32 v[64:65], 0
	v_mov_b64_e32 v[66:67], 0
	v_mov_b64_e32 v[68:69], 0
	v_mov_b64_e32 v[70:71], 0
	v_mov_b64_e32 v[72:73], 0
	v_mov_b64_e32 v[74:75], 0
	v_mov_b64_e32 v[76:77], 0
	v_mov_b64_e32 v[78:79], 0
	v_mov_b64_e32 v[80:81], 0
	v_mov_b64_e32 v[82:83], 0
	v_mov_b64_e32 v[84:85], 0
	v_mov_b64_e32 v[86:87], 0
	v_mov_b64_e32 v[88:89], 0
	v_mov_b64_e32 v[90:91], 0
	v_mov_b64_e32 v[92:93], 0
	v_mov_b64_e32 v[94:95], 0
	v_mov_b64_e32 v[96:97], 0
	v_mov_b64_e32 v[98:99], 0
	v_mov_b64_e32 v[100:101], 0
	v_mov_b64_e32 v[102:103], 0
	v_mov_b64_e32 v[104:105], 0
	v_mov_b64_e32 v[106:107], 0
	v_mov_b64_e32 v[108:109], 0
	v_mov_b64_e32 v[110:111], 0
	v_mov_b64_e32 v[112:113], 0
	v_mov_b64_e32 v[114:115], 0
	v_mov_b64_e32 v[116:117], 0
	v_mov_b64_e32 v[118:119], 0
	v_mov_b64_e32 v[120:121], 0
	v_mov_b64_e32 v[122:123], 0
	v_mov_b64_e32 v[124:125], 0
	v_mov_b64_e32 v[126:127], 0
	s_andn2_b64 vcc, exec, s[20:21]
	s_waitcnt vmcnt(0)
	s_waitcnt lgkmcnt(0)
	.p2align 8
	s_cbranch_vccnz .LBB0_265
	s_add_u32 s40, s40, 0x80
	s_addc_u32 s41, s41, 0
	s_add_u32 s33, s42, 0x100
	s_addc_u32 s38, s43, 0
	s_mov_b32 s42, 0
	s_branch .LBB0_264
	.p2align 8

; template <class Epi, class Sched, bool ALIGN_EPI = false, bool SP2 = false>
; __device__ __forceinline__ void gemm_phase(PG8_LAS unsigned char* lds, const Gemm g, const Sched& S, const Epi& E) {
;     ...
;         asm volatile(".p2align 8");
;         for (int t = 0; t < nt; t += 2) {
;             const bool last = (t == nt - 2);
;             const char* a1 = cA + (size_t)(t + 1) * kstep;
;             const char* a2 = last ? nA : cA + (size_t)(t + 2) * kstep; const char* b2 = last ? nB : cB + (size_t)(t + 2) * kstep;
;             const char* a3 = a2 + kstep; const char* b3 = b2 + kstep;
;     ...
; #pragma unroll
;         for (int a = 0; a < 2; ++a)
; #pragma unroll
;             for (int b = 0; b < 2; ++b)
; #pragma unroll
;                 for (int m = 0; m < 4; ++m)
; #pragma unroll
;                     for (int n = 0; n < 2; ++n) acc[a][b][m][n] = (f32x4){0.f, 0.f, 0.f, 0.f};
;         cur = nxt; cA = nA; cB = nB; ++ui;
.LBB0_282:
	v_mov_b64_e32 v[0:1], 0
	v_mov_b64_e32 v[2:3], 0
	v_mov_b64_e32 v[4:5], 0
	v_mov_b64_e32 v[6:7], 0
	v_mov_b64_e32 v[8:9], 0
	v_mov_b64_e32 v[10:11], 0
	v_mov_b64_e32 v[12:13], 0
	v_mov_b64_e32 v[14:15], 0
	v_mov_b64_e32 v[16:17], 0
	v_mov_b64_e32 v[18:19], 0
	v_mov_b64_e32 v[20:21], 0
	v_mov_b64_e32 v[22:23], 0
	v_mov_b64_e32 v[24:25], 0
	v_mov_b64_e32 v[26:27], 0
	v_mov_b64_e32 v[28:29], 0
	v_mov_b64_e32 v[30:31], 0
	v_mov_b64_e32 v[32:33], 0
	v_mov_b64_e32 v[34:35], 0
	v_mov_b64_e32 v[36:37], 0
	v_mov_b64_e32 v[38:39], 0
	v_mov_b64_e32 v[40:41], 0
	v_mov_b64_e32 v[42:43], 0
	v_mov_b64_e32 v[44:45], 0
	v_mov_b64_e32 v[46:47], 0
	v_mov_b64_e32 v[48:49], 0
	v_mov_b64_e32 v[50:51], 0
	v_mov_b64_e32 v[52:53], 0
	v_mov_b64_e32 v[54:55], 0
	v_mov_b64_e32 v[56:57], 0
	v_mov_b64_e32 v[58:59], 0
	v_mov_b64_e32 v[60:61], 0
	v_mov_b64_e32 v[62:63], 0
	v_mov_b64_e32 v[64:65], 0
	v_mov_b64_e32 v[66:67], 0
	v_mov_b64_e32 v[68:69], 0
	v_mov_b64_e32 v[70:71], 0
	v_mov_b64_e32 v[72:73], 0
	v_mov_b64_e32 v[74:75], 0
	v_mov_b64_e32 v[76:77], 0
	v_mov_b64_e32 v[78:79], 0
	v_mov_b64_e32 v[80:81], 0
	v_mov_b64_e32 v[82:83], 0
	v_mov_b64_e32 v[84:85], 0
	v_mov_b64_e32 v[86:87], 0
	v_mov_b64_e32 v[88:89], 0
	v_mov_b64_e32 v[90:91], 0
	v_mov_b64_e32 v[92:93], 0
	v_mov_b64_e32 v[94:95], 0
	v_mov_b64_e32 v[96:97], 0
	v_mov_b64_e32 v[98:99], 0
	v_mov_b64_e32 v[100:101], 0
	v_mov_b64_e32 v[102:103], 0
	v_mov_b64_e32 v[104:105], 0
	v_mov_b64_e32 v[106:107], 0
	v_mov_b64_e32 v[108:109], 0
	v_mov_b64_e32 v[110:111], 0
	v_mov_b64_e32 v[112:113], 0
	v_mov_b64_e32 v[114:115], 0
	v_mov_b64_e32 v[116:117], 0
	v_mov_b64_e32 v[118:119], 0
	v_mov_b64_e32 v[120:121], 0
	v_mov_b64_e32 v[122:123], 0
	v_mov_b64_e32 v[124:125], 0
	v_mov_b64_e32 v[126:127], 0
	s_and_b64 vcc, exec, s[6:7]
	s_waitcnt lgkmcnt(0)
	.p2align 8
	s_cbranch_vccnz .LBB0_285
	s_add_u32 s60, s60, 0x80
	s_addc_u32 s61, s61, 0
	s_add_u32 s33, s62, 0x100
	s_addc_u32 s89, s63, 0
	s_mov_b32 s62, 0
	s_branch .LBB0_284
	.p2align 8

; template <class Epi, class Sched, bool ALIGN_EPI = false, bool SP2 = false>
; __device__ __forceinline__ void gemm_phase(PG8_LAS unsigned char* lds, const Gemm g, const Sched& S, const Epi& E) {
;     ...
;         asm volatile(".p2align 8");
;         for (int t = 0; t < nt; t += 2) {
;             const bool last = (t == nt - 2);
;             const char* a1 = cA + (size_t)(t + 1) * kstep;
;             const char* a2 = last ? nA : cA + (size_t)(t + 2) * kstep; const char* b2 = last ? nB : cB + (size_t)(t + 2) * kstep;
;             const char* a3 = a2 + kstep; const char* b3 = b2 + kstep;
;     ...
; #pragma unroll
;         for (int a = 0; a < 2; ++a)
; #pragma unroll
;             for (int b = 0; b < 2; ++b)
; #pragma unroll
;                 for (int m = 0; m < 4; ++m)
; #pragma unroll
;                     for (int n = 0; n < 2; ++n) acc[a][b][m][n] = (f32x4){0.f, 0.f, 0.f, 0.f};
;         cur = nxt; cA = nA; cB = nB; ++ui;
.LBB0_366:
	v_mov_b64_e32 v[64:65], 0
	v_mov_b64_e32 v[66:67], 0
	v_mov_b64_e32 v[68:69], 0
	v_mov_b64_e32 v[70:71], 0
	v_mov_b64_e32 v[72:73], 0
	v_mov_b64_e32 v[74:75], 0
	v_mov_b64_e32 v[76:77], 0
	v_mov_b64_e32 v[78:79], 0
	v_mov_b64_e32 v[80:81], 0
	v_mov_b64_e32 v[82:83], 0
	v_mov_b64_e32 v[84:85], 0
	v_mov_b64_e32 v[86:87], 0
	v_mov_b64_e32 v[88:89], 0
	v_mov_b64_e32 v[90:91], 0
	v_mov_b64_e32 v[92:93], 0
	v_mov_b64_e32 v[94:95], 0
	v_mov_b64_e32 v[96:97], 0
	v_mov_b64_e32 v[98:99], 0
	v_mov_b64_e32 v[100:101], 0
	v_mov_b64_e32 v[102:103], 0
	v_mov_b64_e32 v[104:105], 0
	v_mov_b64_e32 v[106:107], 0
	v_mov_b64_e32 v[108:109], 0
	v_mov_b64_e32 v[110:111], 0
	v_mov_b64_e32 v[112:113], 0
	v_mov_b64_e32 v[114:115], 0
	v_mov_b64_e32 v[116:117], 0
	v_mov_b64_e32 v[118:119], 0
	v_mov_b64_e32 v[120:121], 0
	v_mov_b64_e32 v[122:123], 0
	v_mov_b64_e32 v[124:125], 0
	v_mov_b64_e32 v[126:127], 0
	v_mov_b64_e32 v[144:145], 0
	v_mov_b64_e32 v[146:147], 0
	v_mov_b64_e32 v[148:149], 0
	v_mov_b64_e32 v[150:151], 0
	v_mov_b64_e32 v[154:155], 0
	v_mov_b64_e32 v[156:157], 0
	v_mov_b64_e32 v[158:159], 0
	v_mov_b64_e32 v[160:161], 0
	v_mov_b64_e32 v[164:165], 0
	v_mov_b64_e32 v[166:167], 0
	v_mov_b64_e32 v[168:169], 0
	v_mov_b64_e32 v[170:171], 0
	v_mov_b64_e32 v[172:173], 0
	v_mov_b64_e32 v[174:175], 0
	v_mov_b64_e32 v[176:177], 0
	v_mov_b64_e32 v[178:179], 0
	v_mov_b64_e32 v[184:185], 0
	v_mov_b64_e32 v[186:187], 0
	v_mov_b64_e32 v[188:189], 0
	v_mov_b64_e32 v[190:191], 0
	v_mov_b64_e32 v[194:195], 0
	v_mov_b64_e32 v[196:197], 0
	v_mov_b64_e32 v[198:199], 0
	v_mov_b64_e32 v[200:201], 0
	v_mov_b64_e32 v[208:209], 0
	v_mov_b64_e32 v[212:213], 0
	v_mov_b64_e32 v[214:215], 0
	v_mov_b64_e32 v[216:217], 0
	v_mov_b64_e32 v[222:223], 0
	v_mov_b64_e32 v[224:225], 0
	v_mov_b64_e32 v[226:227], 0
	v_mov_b64_e32 v[228:229], 0
	s_andn2_b64 vcc, exec, s[40:41]
	.p2align 8
	s_cbranch_vccnz .LBB0_370
	s_add_u32 s58, s58, 0x80
	s_addc_u32 s59, s59, 0
	s_add_u32 s4, s60, 0x100
	v_mov_b64_e32 v[0:1], 0
	v_mov_b64_e32 v[2:3], 0
	v_mov_b64_e32 v[4:5], 0
	v_mov_b64_e32 v[6:7], 0
	v_mov_b64_e32 v[8:9], 0
	v_mov_b64_e32 v[10:11], 0
	v_mov_b64_e32 v[12:13], 0
	v_mov_b64_e32 v[14:15], 0
	v_mov_b64_e32 v[16:17], 0
	v_mov_b64_e32 v[18:19], 0
	v_mov_b64_e32 v[20:21], 0
	v_mov_b64_e32 v[22:23], 0
	v_mov_b64_e32 v[24:25], 0
	v_mov_b64_e32 v[26:27], 0
	v_mov_b64_e32 v[28:29], 0
	v_mov_b64_e32 v[30:31], 0
	v_mov_b64_e32 v[32:33], 0
	v_mov_b64_e32 v[34:35], 0
	v_mov_b64_e32 v[36:37], 0
	v_mov_b64_e32 v[38:39], 0
	v_mov_b64_e32 v[40:41], 0
	v_mov_b64_e32 v[42:43], 0
	v_mov_b64_e32 v[44:45], 0
	v_mov_b64_e32 v[46:47], 0
	v_mov_b64_e32 v[48:49], 0
	v_mov_b64_e32 v[50:51], 0
	v_mov_b64_e32 v[52:53], 0
	v_mov_b64_e32 v[54:55], 0
	v_mov_b64_e32 v[56:57], 0
	v_mov_b64_e32 v[58:59], 0
	v_mov_b64_e32 v[60:61], 0
	v_mov_b64_e32 v[62:63], 0
	v_mov_b64_e32 v[64:65], 0
	v_mov_b64_e32 v[66:67], 0
	v_mov_b64_e32 v[68:69], 0
	v_mov_b64_e32 v[70:71], 0
	v_mov_b64_e32 v[72:73], 0
	v_mov_b64_e32 v[74:75], 0
	v_mov_b64_e32 v[76:77], 0
	v_mov_b64_e32 v[78:79], 0
	v_mov_b64_e32 v[80:81], 0
	v_mov_b64_e32 v[82:83], 0
	v_mov_b64_e32 v[84:85], 0
	v_mov_b64_e32 v[86:87], 0
	v_mov_b64_e32 v[88:89], 0
	v_mov_b64_e32 v[90:91], 0
	v_mov_b64_e32 v[92:93], 0
	v_mov_b64_e32 v[94:95], 0
	v_mov_b64_e32 v[96:97], 0
	v_mov_b64_e32 v[98:99], 0
	v_mov_b64_e32 v[100:101], 0
	v_mov_b64_e32 v[102:103], 0
	v_mov_b64_e32 v[104:105], 0
	v_mov_b64_e32 v[106:107], 0
	v_mov_b64_e32 v[108:109], 0
	v_mov_b64_e32 v[110:111], 0
	v_mov_b64_e32 v[112:113], 0
	v_mov_b64_e32 v[114:115], 0
	v_mov_b64_e32 v[116:117], 0
	v_mov_b64_e32 v[118:119], 0
	v_mov_b64_e32 v[120:121], 0
	v_mov_b64_e32 v[122:123], 0
	v_mov_b64_e32 v[124:125], 0
	v_mov_b64_e32 v[126:127], 0
	s_addc_u32 s5, s61, 0
	s_mov_b32 s33, 0
	s_waitcnt lgkmcnt(0)
	s_waitcnt vmcnt(0)
	s_branch .LBB0_368
	.p2align 8

; template <class Epi, class Sched, bool ALIGN_EPI = false, bool SP2 = false>
; __device__ __forceinline__ void gemm_phase(PG8_LAS unsigned char* lds, const Gemm g, const Sched& S, const Epi& E) {
;     ...
;         asm volatile(".p2align 8");
;         for (int t = 0; t < nt; t += 2) {
;             const bool last = (t == nt - 2);
;             const char* a1 = cA + (size_t)(t + 1) * kstep;
;             const char* a2 = last ? nA : cA + (size_t)(t + 2) * kstep; const char* b2 = last ? nB : cB + (size_t)(t + 2) * kstep;
;             const char* a3 = a2 + kstep; const char* b3 = b2 + kstep;
;     ...
; #pragma unroll
;         for (int a = 0; a < 2; ++a)
; #pragma unroll
;             for (int b = 0; b < 2; ++b)
; #pragma unroll
;                 for (int m = 0; m < 4; ++m)
; #pragma unroll
;                     for (int n = 0; n < 2; ++n) acc[a][b][m][n] = (f32x4){0.f, 0.f, 0.f, 0.f};
;         cur = nxt; cA = nA; cB = nB; ++ui;
.LBB0_471:
	v_mov_b64_e32 v[0:1], 0
	v_mov_b64_e32 v[2:3], 0
	v_mov_b64_e32 v[4:5], 0
	v_mov_b64_e32 v[6:7], 0
	v_mov_b64_e32 v[8:9], 0
	v_mov_b64_e32 v[10:11], 0
	v_mov_b64_e32 v[12:13], 0
	v_mov_b64_e32 v[14:15], 0
	v_mov_b64_e32 v[16:17], 0
	v_mov_b64_e32 v[18:19], 0
	v_mov_b64_e32 v[20:21], 0
	v_mov_b64_e32 v[22:23], 0
	v_mov_b64_e32 v[24:25], 0
	v_mov_b64_e32 v[26:27], 0
	v_mov_b64_e32 v[28:29], 0
	v_mov_b64_e32 v[30:31], 0
	v_mov_b64_e32 v[32:33], 0
	v_mov_b64_e32 v[34:35], 0
	v_mov_b64_e32 v[36:37], 0
	v_mov_b64_e32 v[38:39], 0
	v_mov_b64_e32 v[40:41], 0
	v_mov_b64_e32 v[42:43], 0
	v_mov_b64_e32 v[44:45], 0
	v_mov_b64_e32 v[46:47], 0
	v_mov_b64_e32 v[48:49], 0
	v_mov_b64_e32 v[50:51], 0
	v_mov_b64_e32 v[52:53], 0
	v_mov_b64_e32 v[54:55], 0
	v_mov_b64_e32 v[56:57], 0
	v_mov_b64_e32 v[58:59], 0
	v_mov_b64_e32 v[60:61], 0
	v_mov_b64_e32 v[62:63], 0
	v_mov_b64_e32 v[64:65], 0
	v_mov_b64_e32 v[66:67], 0
	v_mov_b64_e32 v[68:69], 0
	v_mov_b64_e32 v[70:71], 0
	v_mov_b64_e32 v[72:73], 0
	v_mov_b64_e32 v[74:75], 0
	v_mov_b64_e32 v[76:77], 0
	v_mov_b64_e32 v[78:79], 0
	v_mov_b64_e32 v[80:81], 0
	v_mov_b64_e32 v[82:83], 0
	v_mov_b64_e32 v[84:85], 0
	v_mov_b64_e32 v[86:87], 0
	v_mov_b64_e32 v[88:89], 0
	v_mov_b64_e32 v[90:91], 0
	v_mov_b64_e32 v[92:93], 0
	v_mov_b64_e32 v[94:95], 0
	v_mov_b64_e32 v[96:97], 0
	v_mov_b64_e32 v[98:99], 0
	v_mov_b64_e32 v[100:101], 0
	v_mov_b64_e32 v[102:103], 0
	v_mov_b64_e32 v[104:105], 0
	v_mov_b64_e32 v[106:107], 0
	v_mov_b64_e32 v[108:109], 0
	v_mov_b64_e32 v[110:111], 0
	v_mov_b64_e32 v[112:113], 0
	v_mov_b64_e32 v[114:115], 0
	v_mov_b64_e32 v[116:117], 0
	v_mov_b64_e32 v[118:119], 0
	v_mov_b64_e32 v[120:121], 0
	v_mov_b64_e32 v[122:123], 0
	v_mov_b64_e32 v[124:125], 0
	v_mov_b64_e32 v[126:127], 0
	s_andn2_b64 vcc, exec, s[56:57]
	s_waitcnt vmcnt(0)
	s_waitcnt lgkmcnt(0)
	.p2align 8
	s_cbranch_vccnz .LBB0_474
	s_add_u32 s10, s14, 0x80
	s_addc_u32 s11, s15, 0
	s_add_u32 s5, s12, 0x100
	s_addc_u32 s14, s13, 0
	s_mov_b32 s12, 0
	s_branch .LBB0_473
	.p2align 8

; template <class Epi, class Sched, bool ALIGN_EPI = false, bool SP2 = false>
; __device__ __forceinline__ void gemm_phase(PG8_LAS unsigned char* lds, const Gemm g, const Sched& S, const Epi& E) {
;     ...
;         asm volatile(".p2align 8");
;         for (int t = 0; t < nt; t += 2) {
;             const bool last = (t == nt - 2);
;             const char* a1 = cA + (size_t)(t + 1) * kstep;
;             const char* a2 = last ? nA : cA + (size_t)(t + 2) * kstep; const char* b2 = last ? nB : cB + (size_t)(t + 2) * kstep;
;             const char* a3 = a2 + kstep; const char* b3 = b2 + kstep;
;     ...
; #pragma unroll
;         for (int a = 0; a < 2; ++a)
; #pragma unroll
;             for (int b = 0; b < 2; ++b)
; #pragma unroll
;                 for (int m = 0; m < 4; ++m)
; #pragma unroll
;                     for (int n = 0; n < 2; ++n) acc[a][b][m][n] = (f32x4){0.f, 0.f, 0.f, 0.f};
;         cur = nxt; cA = nA; cB = nB; ++ui;
.LBB0_631:
	v_mov_b64_e32 v[0:1], 0
	v_mov_b64_e32 v[2:3], 0
	v_mov_b64_e32 v[4:5], 0
	v_mov_b64_e32 v[6:7], 0
	v_mov_b64_e32 v[8:9], 0
	v_mov_b64_e32 v[10:11], 0
	v_mov_b64_e32 v[12:13], 0
	v_mov_b64_e32 v[14:15], 0
	v_mov_b64_e32 v[16:17], 0
	v_mov_b64_e32 v[18:19], 0
	v_mov_b64_e32 v[20:21], 0
	v_mov_b64_e32 v[22:23], 0
	v_mov_b64_e32 v[24:25], 0
	v_mov_b64_e32 v[26:27], 0
	v_mov_b64_e32 v[28:29], 0
	v_mov_b64_e32 v[30:31], 0
	v_mov_b64_e32 v[32:33], 0
	v_mov_b64_e32 v[34:35], 0
	v_mov_b64_e32 v[36:37], 0
	v_mov_b64_e32 v[38:39], 0
	v_mov_b64_e32 v[40:41], 0
	v_mov_b64_e32 v[42:43], 0
	v_mov_b64_e32 v[44:45], 0
	v_mov_b64_e32 v[46:47], 0
	v_mov_b64_e32 v[48:49], 0
	v_mov_b64_e32 v[50:51], 0
	v_mov_b64_e32 v[52:53], 0
	v_mov_b64_e32 v[54:55], 0
	v_mov_b64_e32 v[56:57], 0
	v_mov_b64_e32 v[58:59], 0
	v_mov_b64_e32 v[60:61], 0
	v_mov_b64_e32 v[62:63], 0
	v_mov_b64_e32 v[64:65], 0
	v_mov_b64_e32 v[66:67], 0
	v_mov_b64_e32 v[68:69], 0
	v_mov_b64_e32 v[70:71], 0
	v_mov_b64_e32 v[72:73], 0
	v_mov_b64_e32 v[74:75], 0
	v_mov_b64_e32 v[76:77], 0
	v_mov_b64_e32 v[78:79], 0
	v_mov_b64_e32 v[80:81], 0
	v_mov_b64_e32 v[82:83], 0
	v_mov_b64_e32 v[84:85], 0
	v_mov_b64_e32 v[86:87], 0
	v_mov_b64_e32 v[88:89], 0
	v_mov_b64_e32 v[90:91], 0
	v_mov_b64_e32 v[92:93], 0
	v_mov_b64_e32 v[94:95], 0
	v_mov_b64_e32 v[96:97], 0
	v_mov_b64_e32 v[98:99], 0
	v_mov_b64_e32 v[100:101], 0
	v_mov_b64_e32 v[102:103], 0
	v_mov_b64_e32 v[104:105], 0
	v_mov_b64_e32 v[106:107], 0
	v_mov_b64_e32 v[108:109], 0
	v_mov_b64_e32 v[110:111], 0
	v_mov_b64_e32 v[112:113], 0
	v_mov_b64_e32 v[114:115], 0
	v_mov_b64_e32 v[116:117], 0
	v_mov_b64_e32 v[118:119], 0
	v_mov_b64_e32 v[120:121], 0
	v_mov_b64_e32 v[122:123], 0
	v_mov_b64_e32 v[124:125], 0
	v_mov_b64_e32 v[126:127], 0
	s_and_b64 vcc, exec, s[6:7]
	.p2align 8
	s_cbranch_vccnz .LBB0_634
	s_add_u32 s58, s58, 0x80
	s_addc_u32 s59, s59, 0
	s_add_u32 s33, s60, 0x100
	s_addc_u32 s89, s61, 0
	s_mov_b32 s60, 0
	s_branch .LBB0_633
	.p2align 8

; template <class Epi, class Sched, bool ALIGN_EPI = false, bool SP2 = false>
; __device__ __forceinline__ void gemm_phase(PG8_LAS unsigned char* lds, const Gemm g, const Sched& S, const Epi& E) {
;     ...
;         asm volatile(".p2align 8");
;         for (int t = 0; t < nt; t += 2) {
;             const bool last = (t == nt - 2);
;             const char* a1 = cA + (size_t)(t + 1) * kstep;
;             const char* a2 = last ? nA : cA + (size_t)(t + 2) * kstep; const char* b2 = last ? nB : cB + (size_t)(t + 2) * kstep;
;             const char* a3 = a2 + kstep; const char* b3 = b2 + kstep;
;     ...
; #pragma unroll
;         for (int a = 0; a < 2; ++a)
; #pragma unroll
;             for (int b = 0; b < 2; ++b)
; #pragma unroll
;                 for (int m = 0; m < 4; ++m)
; #pragma unroll
;                     for (int n = 0; n < 2; ++n) acc[a][b][m][n] = (f32x4){0.f, 0.f, 0.f, 0.f};
;         cur = nxt; cA = nA; cB = nB; ++ui;
.LBB0_919:
	v_mov_b64_e32 v[0:1], 0
	v_mov_b64_e32 v[2:3], 0
	v_mov_b64_e32 v[4:5], 0
	v_mov_b64_e32 v[6:7], 0
	v_mov_b64_e32 v[8:9], 0
	v_mov_b64_e32 v[10:11], 0
	v_mov_b64_e32 v[12:13], 0
	v_mov_b64_e32 v[14:15], 0
	v_mov_b64_e32 v[16:17], 0
	v_mov_b64_e32 v[18:19], 0
	v_mov_b64_e32 v[20:21], 0
	v_mov_b64_e32 v[22:23], 0
	v_mov_b64_e32 v[24:25], 0
	v_mov_b64_e32 v[26:27], 0
	v_mov_b64_e32 v[28:29], 0
	v_mov_b64_e32 v[30:31], 0
	v_mov_b64_e32 v[32:33], 0
	v_mov_b64_e32 v[34:35], 0
	v_mov_b64_e32 v[36:37], 0
	v_mov_b64_e32 v[38:39], 0
	v_mov_b64_e32 v[40:41], 0
	v_mov_b64_e32 v[42:43], 0
	v_mov_b64_e32 v[44:45], 0
	v_mov_b64_e32 v[46:47], 0
	v_mov_b64_e32 v[48:49], 0
	v_mov_b64_e32 v[50:51], 0
	v_mov_b64_e32 v[52:53], 0
	v_mov_b64_e32 v[54:55], 0
	v_mov_b64_e32 v[56:57], 0
	v_mov_b64_e32 v[58:59], 0
	v_mov_b64_e32 v[60:61], 0
	v_mov_b64_e32 v[62:63], 0
	v_mov_b64_e32 v[64:65], 0
	v_mov_b64_e32 v[66:67], 0
	v_mov_b64_e32 v[68:69], 0
	v_mov_b64_e32 v[70:71], 0
	v_mov_b64_e32 v[72:73], 0
	v_mov_b64_e32 v[74:75], 0
	v_mov_b64_e32 v[76:77], 0
	v_mov_b64_e32 v[78:79], 0
	v_mov_b64_e32 v[80:81], 0
	v_mov_b64_e32 v[82:83], 0
	v_mov_b64_e32 v[84:85], 0
	v_mov_b64_e32 v[86:87], 0
	v_mov_b64_e32 v[88:89], 0
	v_mov_b64_e32 v[90:91], 0
	v_mov_b64_e32 v[92:93], 0
	v_mov_b64_e32 v[94:95], 0
	v_mov_b64_e32 v[96:97], 0
	v_mov_b64_e32 v[98:99], 0
	v_mov_b64_e32 v[100:101], 0
	v_mov_b64_e32 v[102:103], 0
	v_mov_b64_e32 v[104:105], 0
	v_mov_b64_e32 v[106:107], 0
	v_mov_b64_e32 v[108:109], 0
	v_mov_b64_e32 v[110:111], 0
	v_mov_b64_e32 v[112:113], 0
	v_mov_b64_e32 v[114:115], 0
	v_mov_b64_e32 v[116:117], 0
	v_mov_b64_e32 v[118:119], 0
	v_mov_b64_e32 v[120:121], 0
	v_mov_b64_e32 v[122:123], 0
	v_mov_b64_e32 v[124:125], 0
	v_mov_b64_e32 v[126:127], 0
	s_andn2_b64 vcc, exec, s[36:37]
	s_waitcnt vmcnt(0)
	.p2align 8
	s_cbranch_vccnz .LBB0_922
	s_add_u32 s42, s42, 0x80
	s_addc_u32 s43, s43, 0
	s_add_u32 s5, s58, 0x100
	s_addc_u32 s33, s59, 0
	s_mov_b32 s58, 0
	s_branch .LBB0_921
	.p2align 8

; template <class Epi, class Sched, bool ALIGN_EPI = false, bool SP2 = false>
; __device__ __forceinline__ void gemm_phase(PG8_LAS unsigned char* lds, const Gemm g, const Sched& S, const Epi& E) {
;     ...
;         asm volatile(".p2align 8");
;         for (int t = 0; t < nt; t += 2) {
;             const bool last = (t == nt - 2);
;             const char* a1 = cA + (size_t)(t + 1) * kstep;
;             const char* a2 = last ? nA : cA + (size_t)(t + 2) * kstep; const char* b2 = last ? nB : cB + (size_t)(t + 2) * kstep;
;             const char* a3 = a2 + kstep; const char* b3 = b2 + kstep;
;     ...
; #pragma unroll
;         for (int a = 0; a < 2; ++a)
; #pragma unroll
;             for (int b = 0; b < 2; ++b)
; #pragma unroll
;                 for (int m = 0; m < 4; ++m)
; #pragma unroll
;                     for (int n = 0; n < 2; ++n) acc[a][b][m][n] = (f32x4){0.f, 0.f, 0.f, 0.f};
;         cur = nxt; cA = nA; cB = nB; ++ui;
.LBB0_1012:
	v_mov_b64_e32 v[0:1], 0
	v_mov_b64_e32 v[2:3], 0
	v_mov_b64_e32 v[4:5], 0
	v_mov_b64_e32 v[6:7], 0
	v_mov_b64_e32 v[8:9], 0
	v_mov_b64_e32 v[10:11], 0
	v_mov_b64_e32 v[12:13], 0
	v_mov_b64_e32 v[14:15], 0
	v_mov_b64_e32 v[16:17], 0
	v_mov_b64_e32 v[18:19], 0
	v_mov_b64_e32 v[20:21], 0
	v_mov_b64_e32 v[22:23], 0
	v_mov_b64_e32 v[24:25], 0
	v_mov_b64_e32 v[26:27], 0
	v_mov_b64_e32 v[28:29], 0
	v_mov_b64_e32 v[30:31], 0
	v_mov_b64_e32 v[32:33], 0
	v_mov_b64_e32 v[34:35], 0
	v_mov_b64_e32 v[36:37], 0
	v_mov_b64_e32 v[38:39], 0
	v_mov_b64_e32 v[40:41], 0
	v_mov_b64_e32 v[42:43], 0
	v_mov_b64_e32 v[44:45], 0
	v_mov_b64_e32 v[46:47], 0
	v_mov_b64_e32 v[48:49], 0
	v_mov_b64_e32 v[50:51], 0
	v_mov_b64_e32 v[52:53], 0
	v_mov_b64_e32 v[54:55], 0
	v_mov_b64_e32 v[56:57], 0
	v_mov_b64_e32 v[58:59], 0
	v_mov_b64_e32 v[60:61], 0
	v_mov_b64_e32 v[62:63], 0
	v_mov_b64_e32 v[64:65], 0
	v_mov_b64_e32 v[66:67], 0
	v_mov_b64_e32 v[68:69], 0
	v_mov_b64_e32 v[70:71], 0
	v_mov_b64_e32 v[72:73], 0
	v_mov_b64_e32 v[74:75], 0
	v_mov_b64_e32 v[76:77], 0
	v_mov_b64_e32 v[78:79], 0
	v_mov_b64_e32 v[80:81], 0
	v_mov_b64_e32 v[82:83], 0
	v_mov_b64_e32 v[84:85], 0
	v_mov_b64_e32 v[86:87], 0
	v_mov_b64_e32 v[88:89], 0
	v_mov_b64_e32 v[90:91], 0
	v_mov_b64_e32 v[92:93], 0
	v_mov_b64_e32 v[94:95], 0
	v_mov_b64_e32 v[96:97], 0
	v_mov_b64_e32 v[98:99], 0
	v_mov_b64_e32 v[100:101], 0
	v_mov_b64_e32 v[102:103], 0
	v_mov_b64_e32 v[104:105], 0
	v_mov_b64_e32 v[106:107], 0
	v_mov_b64_e32 v[108:109], 0
	v_mov_b64_e32 v[110:111], 0
	v_mov_b64_e32 v[112:113], 0
	v_mov_b64_e32 v[114:115], 0
	v_mov_b64_e32 v[116:117], 0
	v_mov_b64_e32 v[118:119], 0
	v_mov_b64_e32 v[120:121], 0
	v_mov_b64_e32 v[122:123], 0
	v_mov_b64_e32 v[124:125], 0
	v_mov_b64_e32 v[126:127], 0
	s_andn2_b64 vcc, exec, s[18:19]
	s_waitcnt vmcnt(0)
	.p2align 8
	s_cbranch_vccnz .LBB0_1015
	s_add_u32 s36, s36, 0x80
	s_addc_u32 s37, s37, 0
	s_add_u32 s33, s38, 0x100
	s_addc_u32 s70, s39, 0
	s_mov_b32 s38, 0
	s_branch .LBB0_1014
	.p2align 8

; template <class Epi, class Sched, bool ALIGN_EPI = false, bool SP2 = false>
; __device__ __forceinline__ void gemm_phase(PG8_LAS unsigned char* lds, const Gemm g, const Sched& S, const Epi& E) {
;     ...
;         asm volatile(".p2align 8");
;         for (int t = 0; t < nt; t += 2) {
;             const bool last = (t == nt - 2);
;             const char* a1 = cA + (size_t)(t + 1) * kstep;
;             const char* a2 = last ? nA : cA + (size_t)(t + 2) * kstep; const char* b2 = last ? nB : cB + (size_t)(t + 2) * kstep;
;             const char* a3 = a2 + kstep; const char* b3 = b2 + kstep;
;     ...
; #pragma unroll
;         for (int a = 0; a < 2; ++a)
; #pragma unroll
;             for (int b = 0; b < 2; ++b)
; #pragma unroll
;                 for (int m = 0; m < 4; ++m)
; #pragma unroll
;                     for (int n = 0; n < 2; ++n) acc[a][b][m][n] = (f32x4){0.f, 0.f, 0.f, 0.f};
;         cur = nxt; cA = nA; cB = nB; ++ui;
.LBB0_1032:
	v_mov_b64_e32 v[0:1], 0
	v_mov_b64_e32 v[2:3], 0
	v_mov_b64_e32 v[4:5], 0
	v_mov_b64_e32 v[6:7], 0
	v_mov_b64_e32 v[8:9], 0
	v_mov_b64_e32 v[10:11], 0
	v_mov_b64_e32 v[12:13], 0
	v_mov_b64_e32 v[14:15], 0
	v_mov_b64_e32 v[16:17], 0
	v_mov_b64_e32 v[18:19], 0
	v_mov_b64_e32 v[20:21], 0
	v_mov_b64_e32 v[22:23], 0
	v_mov_b64_e32 v[24:25], 0
	v_mov_b64_e32 v[26:27], 0
	v_mov_b64_e32 v[28:29], 0
	v_mov_b64_e32 v[30:31], 0
	v_mov_b64_e32 v[32:33], 0
	v_mov_b64_e32 v[34:35], 0
	v_mov_b64_e32 v[36:37], 0
	v_mov_b64_e32 v[38:39], 0
	v_mov_b64_e32 v[40:41], 0
	v_mov_b64_e32 v[42:43], 0
	v_mov_b64_e32 v[44:45], 0
	v_mov_b64_e32 v[46:47], 0
	v_mov_b64_e32 v[48:49], 0
	v_mov_b64_e32 v[50:51], 0
	v_mov_b64_e32 v[52:53], 0
	v_mov_b64_e32 v[54:55], 0
	v_mov_b64_e32 v[56:57], 0
	v_mov_b64_e32 v[58:59], 0
	v_mov_b64_e32 v[60:61], 0
	v_mov_b64_e32 v[62:63], 0
	v_mov_b64_e32 v[64:65], 0
	v_mov_b64_e32 v[66:67], 0
	v_mov_b64_e32 v[68:69], 0
	v_mov_b64_e32 v[70:71], 0
	v_mov_b64_e32 v[72:73], 0
	v_mov_b64_e32 v[74:75], 0
	v_mov_b64_e32 v[76:77], 0
	v_mov_b64_e32 v[78:79], 0
	v_mov_b64_e32 v[80:81], 0
	v_mov_b64_e32 v[82:83], 0
	v_mov_b64_e32 v[84:85], 0
	v_mov_b64_e32 v[86:87], 0
	v_mov_b64_e32 v[88:89], 0
	v_mov_b64_e32 v[90:91], 0
	v_mov_b64_e32 v[92:93], 0
	v_mov_b64_e32 v[94:95], 0
	v_mov_b64_e32 v[96:97], 0
	v_mov_b64_e32 v[98:99], 0
	v_mov_b64_e32 v[100:101], 0
	v_mov_b64_e32 v[102:103], 0
	v_mov_b64_e32 v[104:105], 0
	v_mov_b64_e32 v[106:107], 0
	v_mov_b64_e32 v[108:109], 0
	v_mov_b64_e32 v[110:111], 0
	v_mov_b64_e32 v[112:113], 0
	v_mov_b64_e32 v[114:115], 0
	v_mov_b64_e32 v[116:117], 0
	v_mov_b64_e32 v[118:119], 0
	v_mov_b64_e32 v[120:121], 0
	v_mov_b64_e32 v[122:123], 0
	v_mov_b64_e32 v[124:125], 0
	v_mov_b64_e32 v[126:127], 0
	s_and_b64 vcc, exec, s[0:1]
	.p2align 8
	s_cbranch_vccnz .LBB0_1035
	s_add_u32 s54, s54, 0x80
	s_addc_u32 s55, s55, 0
	s_add_u32 s33, s56, 0x100
	s_addc_u32 s85, s57, 0
	s_mov_b32 s56, 0
	s_branch .LBB0_1034
	.p2align 8

; template <class Epi, class Sched, bool ALIGN_EPI = false, bool SP2 = false>
; __device__ __forceinline__ void gemm_phase(PG8_LAS unsigned char* lds, const Gemm g, const Sched& S, const Epi& E) {
;     ...
;         asm volatile(".p2align 8");
;         for (int t = 0; t < nt; t += 2) {
;             const bool last = (t == nt - 2);
;             const char* a1 = cA + (size_t)(t + 1) * kstep;
;             const char* a2 = last ? nA : cA + (size_t)(t + 2) * kstep; const char* b2 = last ? nB : cB + (size_t)(t + 2) * kstep;
;             const char* a3 = a2 + kstep; const char* b3 = b2 + kstep;
;     ...
; #pragma unroll
;         for (int a = 0; a < 2; ++a)
; #pragma unroll
;             for (int b = 0; b < 2; ++b)
; #pragma unroll
;                 for (int m = 0; m < 4; ++m)
; #pragma unroll
;                     for (int n = 0; n < 2; ++n) acc[a][b][m][n] = (f32x4){0.f, 0.f, 0.f, 0.f};
;         cur = nxt; cA = nA; cB = nB; ++ui;
.LBB0_1116:
	v_mov_b64_e32 v[64:65], 0
	v_mov_b64_e32 v[66:67], 0
	v_mov_b64_e32 v[68:69], 0
	v_mov_b64_e32 v[70:71], 0
	v_mov_b64_e32 v[72:73], 0
	v_mov_b64_e32 v[74:75], 0
	v_mov_b64_e32 v[76:77], 0
	v_mov_b64_e32 v[78:79], 0
	v_mov_b64_e32 v[80:81], 0
	v_mov_b64_e32 v[82:83], 0
	v_mov_b64_e32 v[84:85], 0
	v_mov_b64_e32 v[86:87], 0
	v_mov_b64_e32 v[88:89], 0
	v_mov_b64_e32 v[90:91], 0
	v_mov_b64_e32 v[92:93], 0
	v_mov_b64_e32 v[94:95], 0
	v_mov_b64_e32 v[96:97], 0
	v_mov_b64_e32 v[98:99], 0
	v_mov_b64_e32 v[100:101], 0
	v_mov_b64_e32 v[102:103], 0
	v_mov_b64_e32 v[104:105], 0
	v_mov_b64_e32 v[106:107], 0
	v_mov_b64_e32 v[108:109], 0
	v_mov_b64_e32 v[110:111], 0
	v_mov_b64_e32 v[112:113], 0
	v_mov_b64_e32 v[114:115], 0
	v_mov_b64_e32 v[116:117], 0
	v_mov_b64_e32 v[118:119], 0
	v_mov_b64_e32 v[120:121], 0
	v_mov_b64_e32 v[122:123], 0
	v_mov_b64_e32 v[124:125], 0
	v_mov_b64_e32 v[126:127], 0
	v_mov_b64_e32 v[142:143], 0
	v_mov_b64_e32 v[144:145], 0
	v_mov_b64_e32 v[146:147], 0
	v_mov_b64_e32 v[148:149], 0
	v_mov_b64_e32 v[152:153], 0
	v_mov_b64_e32 v[154:155], 0
	v_mov_b64_e32 v[156:157], 0
	v_mov_b64_e32 v[158:159], 0
	v_mov_b64_e32 v[162:163], 0
	v_mov_b64_e32 v[164:165], 0
	v_mov_b64_e32 v[166:167], 0
	v_mov_b64_e32 v[168:169], 0
	v_mov_b64_e32 v[170:171], 0
	v_mov_b64_e32 v[172:173], 0
	v_mov_b64_e32 v[174:175], 0
	v_mov_b64_e32 v[176:177], 0
	v_mov_b64_e32 v[182:183], 0
	v_mov_b64_e32 v[184:185], 0
	v_mov_b64_e32 v[186:187], 0
	v_mov_b64_e32 v[188:189], 0
	v_mov_b64_e32 v[190:191], 0
	v_mov_b64_e32 v[194:195], 0
	v_mov_b64_e32 v[196:197], 0
	v_mov_b64_e32 v[198:199], 0
	v_mov_b64_e32 v[206:207], 0
	v_mov_b64_e32 v[210:211], 0
	v_mov_b64_e32 v[212:213], 0
	v_mov_b64_e32 v[214:215], 0
	v_mov_b64_e32 v[220:221], 0
	v_mov_b64_e32 v[222:223], 0
	v_mov_b64_e32 v[224:225], 0
	v_mov_b64_e32 v[226:227], 0
	s_andn2_b64 vcc, exec, s[36:37]
	.p2align 8
	s_cbranch_vccnz .LBB0_1120
	s_add_u32 s42, s42, 0x80
	s_addc_u32 s43, s43, 0
	s_add_u32 s4, s54, 0x100
	v_mov_b64_e32 v[0:1], 0
	v_mov_b64_e32 v[2:3], 0
	v_mov_b64_e32 v[4:5], 0
	v_mov_b64_e32 v[6:7], 0
	v_mov_b64_e32 v[8:9], 0
	v_mov_b64_e32 v[10:11], 0
	v_mov_b64_e32 v[12:13], 0
	v_mov_b64_e32 v[14:15], 0
	v_mov_b64_e32 v[16:17], 0
	v_mov_b64_e32 v[18:19], 0
	v_mov_b64_e32 v[20:21], 0
	v_mov_b64_e32 v[22:23], 0
	v_mov_b64_e32 v[24:25], 0
	v_mov_b64_e32 v[26:27], 0
	v_mov_b64_e32 v[28:29], 0
	v_mov_b64_e32 v[30:31], 0
	v_mov_b64_e32 v[32:33], 0
	v_mov_b64_e32 v[34:35], 0
	v_mov_b64_e32 v[36:37], 0
	v_mov_b64_e32 v[38:39], 0
	v_mov_b64_e32 v[40:41], 0
	v_mov_b64_e32 v[42:43], 0
	v_mov_b64_e32 v[44:45], 0
	v_mov_b64_e32 v[46:47], 0
	v_mov_b64_e32 v[48:49], 0
	v_mov_b64_e32 v[50:51], 0
	v_mov_b64_e32 v[52:53], 0
	v_mov_b64_e32 v[54:55], 0
	v_mov_b64_e32 v[56:57], 0
	v_mov_b64_e32 v[58:59], 0
	v_mov_b64_e32 v[60:61], 0
	v_mov_b64_e32 v[62:63], 0
	v_mov_b64_e32 v[64:65], 0
	v_mov_b64_e32 v[66:67], 0
	v_mov_b64_e32 v[68:69], 0
	v_mov_b64_e32 v[70:71], 0
	v_mov_b64_e32 v[72:73], 0
	v_mov_b64_e32 v[74:75], 0
	v_mov_b64_e32 v[76:77], 0
	v_mov_b64_e32 v[78:79], 0
	v_mov_b64_e32 v[80:81], 0
	v_mov_b64_e32 v[82:83], 0
	v_mov_b64_e32 v[84:85], 0
	v_mov_b64_e32 v[86:87], 0
	v_mov_b64_e32 v[88:89], 0
	v_mov_b64_e32 v[90:91], 0
	v_mov_b64_e32 v[92:93], 0
	v_mov_b64_e32 v[94:95], 0
	v_mov_b64_e32 v[96:97], 0
	v_mov_b64_e32 v[98:99], 0
	v_mov_b64_e32 v[100:101], 0
	v_mov_b64_e32 v[102:103], 0
	v_mov_b64_e32 v[104:105], 0
	v_mov_b64_e32 v[106:107], 0
	v_mov_b64_e32 v[108:109], 0
	v_mov_b64_e32 v[110:111], 0
	v_mov_b64_e32 v[112:113], 0
	v_mov_b64_e32 v[114:115], 0
	v_mov_b64_e32 v[116:117], 0
	v_mov_b64_e32 v[118:119], 0
	v_mov_b64_e32 v[120:121], 0
	v_mov_b64_e32 v[122:123], 0
	v_mov_b64_e32 v[124:125], 0
	v_mov_b64_e32 v[126:127], 0
	s_addc_u32 s5, s55, 0
	s_mov_b32 s33, 0
	s_waitcnt vmcnt(0)
	s_branch .LBB0_1118
	.p2align 8

; template <class Epi, class Sched, bool ALIGN_EPI = false, bool SP2 = false>
; __device__ __forceinline__ void gemm_phase(PG8_LAS unsigned char* lds, const Gemm g, const Sched& S, const Epi& E) {
;     ...
;         asm volatile(".p2align 8");
;         for (int t = 0; t < nt; t += 2) {
;             const bool last = (t == nt - 2);
;             const char* a1 = cA + (size_t)(t + 1) * kstep;
;             const char* a2 = last ? nA : cA + (size_t)(t + 2) * kstep; const char* b2 = last ? nB : cB + (size_t)(t + 2) * kstep;
;             const char* a3 = a2 + kstep; const char* b3 = b2 + kstep;
;     ...
; #pragma unroll
;         for (int a = 0; a < 2; ++a)
; #pragma unroll
;             for (int b = 0; b < 2; ++b)
; #pragma unroll
;                 for (int m = 0; m < 4; ++m)
; #pragma unroll
;                     for (int n = 0; n < 2; ++n) acc[a][b][m][n] = (f32x4){0.f, 0.f, 0.f, 0.f};
;         cur = nxt; cA = nA; cB = nB; ++ui;
.LBB0_1219:
	v_mov_b64_e32 v[0:1], 0
	v_mov_b64_e32 v[2:3], 0
	v_mov_b64_e32 v[4:5], 0
	v_mov_b64_e32 v[6:7], 0
	v_mov_b64_e32 v[8:9], 0
	v_mov_b64_e32 v[10:11], 0
	v_mov_b64_e32 v[12:13], 0
	v_mov_b64_e32 v[14:15], 0
	v_mov_b64_e32 v[16:17], 0
	v_mov_b64_e32 v[18:19], 0
	v_mov_b64_e32 v[20:21], 0
	v_mov_b64_e32 v[22:23], 0
	v_mov_b64_e32 v[24:25], 0
	v_mov_b64_e32 v[26:27], 0
	v_mov_b64_e32 v[28:29], 0
	v_mov_b64_e32 v[30:31], 0
	v_mov_b64_e32 v[32:33], 0
	v_mov_b64_e32 v[34:35], 0
	v_mov_b64_e32 v[36:37], 0
	v_mov_b64_e32 v[38:39], 0
	v_mov_b64_e32 v[40:41], 0
	v_mov_b64_e32 v[42:43], 0
	v_mov_b64_e32 v[44:45], 0
	v_mov_b64_e32 v[46:47], 0
	v_mov_b64_e32 v[48:49], 0
	v_mov_b64_e32 v[50:51], 0
	v_mov_b64_e32 v[52:53], 0
	v_mov_b64_e32 v[54:55], 0
	v_mov_b64_e32 v[56:57], 0
	v_mov_b64_e32 v[58:59], 0
	v_mov_b64_e32 v[60:61], 0
	v_mov_b64_e32 v[62:63], 0
	v_mov_b64_e32 v[64:65], 0
	v_mov_b64_e32 v[66:67], 0
	v_mov_b64_e32 v[68:69], 0
	v_mov_b64_e32 v[70:71], 0
	v_mov_b64_e32 v[72:73], 0
	v_mov_b64_e32 v[74:75], 0
	v_mov_b64_e32 v[76:77], 0
	v_mov_b64_e32 v[78:79], 0
	v_mov_b64_e32 v[80:81], 0
	v_mov_b64_e32 v[82:83], 0
	v_mov_b64_e32 v[84:85], 0
	v_mov_b64_e32 v[86:87], 0
	v_mov_b64_e32 v[88:89], 0
	v_mov_b64_e32 v[90:91], 0
	v_mov_b64_e32 v[92:93], 0
	v_mov_b64_e32 v[94:95], 0
	v_mov_b64_e32 v[96:97], 0
	v_mov_b64_e32 v[98:99], 0
	v_mov_b64_e32 v[100:101], 0
	v_mov_b64_e32 v[102:103], 0
	v_mov_b64_e32 v[104:105], 0
	v_mov_b64_e32 v[106:107], 0
	v_mov_b64_e32 v[108:109], 0
	v_mov_b64_e32 v[110:111], 0
	v_mov_b64_e32 v[112:113], 0
	v_mov_b64_e32 v[114:115], 0
	v_mov_b64_e32 v[116:117], 0
	v_mov_b64_e32 v[118:119], 0
	v_mov_b64_e32 v[120:121], 0
	v_mov_b64_e32 v[122:123], 0
	v_mov_b64_e32 v[124:125], 0
	v_mov_b64_e32 v[126:127], 0
	s_andn2_b64 vcc, exec, s[18:19]
	.p2align 8
	s_cbranch_vccnz .LBB0_1222
	s_add_u32 s42, s42, 0x80
	s_addc_u32 s43, s43, 0
	s_add_u32 s68, s48, 0x100
	s_addc_u32 s69, s49, 0
	s_mov_b32 s48, 0
	s_branch .LBB0_1221
	.p2align 8

; template <class Epi, class Sched, bool ALIGN_EPI = false, bool SP2 = false>
; __device__ __forceinline__ void gemm_phase(PG8_LAS unsigned char* lds, const Gemm g, const Sched& S, const Epi& E) {
;     ...
;         asm volatile(".p2align 8");
;         for (int t = 0; t < nt; t += 2) {
;             const bool last = (t == nt - 2);
;             const char* a1 = cA + (size_t)(t + 1) * kstep;
;             const char* a2 = last ? nA : cA + (size_t)(t + 2) * kstep; const char* b2 = last ? nB : cB + (size_t)(t + 2) * kstep;
;             const char* a3 = a2 + kstep; const char* b3 = b2 + kstep;
;     ...
; #pragma unroll
;         for (int a = 0; a < 2; ++a)
; #pragma unroll
;             for (int b = 0; b < 2; ++b)
; #pragma unroll
;                 for (int m = 0; m < 4; ++m)
; #pragma unroll
;                     for (int n = 0; n < 2; ++n) acc[a][b][m][n] = (f32x4){0.f, 0.f, 0.f, 0.f};
;         cur = nxt; cA = nA; cB = nB; ++ui;
.LBB0_1251:
	v_mov_b64_e32 v[0:1], 0
	v_mov_b64_e32 v[2:3], 0
	v_mov_b64_e32 v[4:5], 0
	v_mov_b64_e32 v[6:7], 0
	v_mov_b64_e32 v[8:9], 0
	v_mov_b64_e32 v[10:11], 0
	v_mov_b64_e32 v[12:13], 0
	v_mov_b64_e32 v[14:15], 0
	v_mov_b64_e32 v[16:17], 0
	v_mov_b64_e32 v[18:19], 0
	v_mov_b64_e32 v[20:21], 0
	v_mov_b64_e32 v[22:23], 0
	v_mov_b64_e32 v[24:25], 0
	v_mov_b64_e32 v[26:27], 0
	v_mov_b64_e32 v[28:29], 0
	v_mov_b64_e32 v[30:31], 0
	v_mov_b64_e32 v[32:33], 0
	v_mov_b64_e32 v[34:35], 0
	v_mov_b64_e32 v[36:37], 0
	v_mov_b64_e32 v[38:39], 0
	v_mov_b64_e32 v[40:41], 0
	v_mov_b64_e32 v[42:43], 0
	v_mov_b64_e32 v[44:45], 0
	v_mov_b64_e32 v[46:47], 0
	v_mov_b64_e32 v[48:49], 0
	v_mov_b64_e32 v[50:51], 0
	v_mov_b64_e32 v[52:53], 0
	v_mov_b64_e32 v[54:55], 0
	v_mov_b64_e32 v[56:57], 0
	v_mov_b64_e32 v[58:59], 0
	v_mov_b64_e32 v[60:61], 0
	v_mov_b64_e32 v[62:63], 0
	v_mov_b64_e32 v[64:65], 0
	v_mov_b64_e32 v[66:67], 0
	v_mov_b64_e32 v[68:69], 0
	v_mov_b64_e32 v[70:71], 0
	v_mov_b64_e32 v[72:73], 0
	v_mov_b64_e32 v[74:75], 0
	v_mov_b64_e32 v[76:77], 0
	v_mov_b64_e32 v[78:79], 0
	v_mov_b64_e32 v[80:81], 0
	v_mov_b64_e32 v[82:83], 0
	v_mov_b64_e32 v[84:85], 0
	v_mov_b64_e32 v[86:87], 0
	v_mov_b64_e32 v[88:89], 0
	v_mov_b64_e32 v[90:91], 0
	v_mov_b64_e32 v[92:93], 0
	v_mov_b64_e32 v[94:95], 0
	v_mov_b64_e32 v[96:97], 0
	v_mov_b64_e32 v[98:99], 0
	v_mov_b64_e32 v[100:101], 0
	v_mov_b64_e32 v[102:103], 0
	v_mov_b64_e32 v[104:105], 0
	v_mov_b64_e32 v[106:107], 0
	v_mov_b64_e32 v[108:109], 0
	v_mov_b64_e32 v[110:111], 0
	v_mov_b64_e32 v[112:113], 0
	v_mov_b64_e32 v[114:115], 0
	v_mov_b64_e32 v[116:117], 0
	v_mov_b64_e32 v[118:119], 0
	v_mov_b64_e32 v[120:121], 0
	v_mov_b64_e32 v[122:123], 0
	v_mov_b64_e32 v[128:129], 0
	v_mov_b64_e32 v[130:131], 0
	s_andn2_b64 vcc, exec, s[16:17]
	.p2align 8
	s_cbranch_vccnz .LBB0_1254
	s_add_u32 s22, s22, 0x80
	s_addc_u32 s23, s23, 0
	s_add_u32 s53, s26, 0x100
	s_addc_u32 s54, s27, 0
	s_mov_b32 s26, 0
	s_branch .LBB0_1253
	.p2align 8
